# LDS-DMA attention loop with the last PV group of each tile deferred past the barrier (hides the post-barrier K fragment latency)
# baseline (speedup 1.0000x reference)
.Lattn_nf_loop:
	ds_read_b128 v[98:101], v82 offset:0
	ds_read_b128 v[102:105], v83 offset:0
	ds_read_b128 v[106:109], v84 offset:0
	ds_read_b128 v[110:113], v85 offset:0
	s_and_b32 s10, s15, 1
	s_xor_b32 s10, s10, 1
	s_lshl_b32 s10, s10, 15
	s_add_i32 s10, s10, s11
	s_add_i32 s6, s10, 0x10000
	s_cmp_eq_u32 s15, 0
	s_cbranch_scc1 .Lattn_nodefer
	v_mfma_f32_32x32x16_bf16 v[18:33], v[196:199], v[118:121], v[18:33]
	v_mfma_f32_32x32x16_bf16 v[34:49], v[216:219], v[118:121], v[34:49]
	v_mfma_f32_32x32x16_bf16 v[50:65], v[200:203], v[118:121], v[50:65]
	v_mfma_f32_32x32x16_bf16 v[66:81], v[204:207], v[118:121], v[66:81]
.Lattn_nodefer:
	s_waitcnt lgkmcnt(3)
	v_mfma_f32_32x32x16_bf16 v[138:153], v[98:101], v[10:13], 0
	ds_read_b128 v[98:101], v82 offset:8192
	s_add_i32 m0, s10, 0x0
	s_nop 0
	global_load_lds_dwordx4 v124, s[64:65]
	s_add_i32 m0, s10, 0x2000
	s_nop 0
	global_load_lds_dwordx4 v124, s[66:67]
	s_waitcnt lgkmcnt(3)
	v_mfma_f32_32x32x16_bf16 v[138:153], v[102:105], v[14:17], v[138:153]
	ds_read_b128 v[102:105], v83 offset:8192
	s_add_i32 m0, s10, 0x4000
	s_nop 0
	global_load_lds_dwordx4 v124, s[68:69]
	s_add_i32 m0, s10, 0x6000
	s_nop 0
	global_load_lds_dwordx4 v124, s[70:71]
	v_add_u32_e32 v124, s36, v124
	s_waitcnt lgkmcnt(3)
	v_mfma_f32_32x32x16_bf16 v[138:153], v[106:109], v[2:5], v[138:153]
	ds_read_b128 v[106:109], v84 offset:8192
	s_add_i32 m0, s6, 0x0
	s_nop 0
	global_load_lds_dwordx4 v125, s[72:73]
	s_add_i32 m0, s6, 0x2000
	s_nop 0
	global_load_lds_dwordx4 v125, s[74:75]
	s_waitcnt lgkmcnt(3)
	v_mfma_f32_32x32x16_bf16 v[138:153], v[110:113], v[6:9], v[138:153]
	ds_read_b128 v[110:113], v85 offset:8192
	s_add_i32 m0, s6, 0x4000
	s_nop 0
	global_load_lds_dwordx4 v125, s[76:77]
	s_add_i32 m0, s6, 0x6000
	s_nop 0
	global_load_lds_dwordx4 v125, s[78:79]
	v_add_u32_e32 v125, s38, v125
	ds_read_b128 v[128:131], v86 offset:0
	ds_read_b128 v[184:187], v86 offset:8192
	ds_read_b128 v[188:191], v86 offset:16384
	ds_read_b128 v[192:195], v86 offset:24576
	s_waitcnt lgkmcnt(7)
	v_mfma_f32_32x32x16_bf16 v[154:169], v[98:101], v[10:13], 0
	ds_read_b128 v[98:101], v82 offset:16384
	v_exp_f32_e32 v138, v138
	v_exp_f32_e32 v139, v139
	v_exp_f32_e32 v140, v140
	v_exp_f32_e32 v141, v141
	v_exp_f32_e32 v142, v142
	v_exp_f32_e32 v143, v143
	s_waitcnt lgkmcnt(7)
	v_mfma_f32_32x32x16_bf16 v[154:169], v[102:105], v[14:17], v[154:169]
	ds_read_b128 v[102:105], v83 offset:16384
	v_exp_f32_e32 v144, v144
	v_exp_f32_e32 v145, v145
	v_add_f32_e32 v122, v138, v122
	v_add_f32_e32 v122, v139, v122
	v_add_f32_e32 v122, v140, v122
	v_add_f32_e32 v122, v141, v122
	v_add_f32_e32 v122, v142, v122
	v_add_f32_e32 v122, v143, v122
	v_add_f32_e32 v122, v144, v122
	v_add_f32_e32 v122, v145, v122
	v_cvt_pk_bf16_f32 v114, v138, v139
	v_cvt_pk_bf16_f32 v115, v140, v141
	v_cvt_pk_bf16_f32 v116, v142, v143
	v_cvt_pk_bf16_f32 v117, v144, v145
	ds_read_b128 v[196:199], v87 offset:0
	ds_read_b128 v[216:219], v87 offset:8192
	ds_read_b128 v[200:203], v87 offset:16384
	ds_read_b128 v[204:207], v87 offset:24576
	s_waitcnt lgkmcnt(11)
	v_mfma_f32_32x32x16_bf16 v[154:169], v[106:109], v[2:5], v[154:169]
	ds_read_b128 v[106:109], v84 offset:16384
	v_exp_f32_e32 v146, v146
	v_exp_f32_e32 v147, v147
	s_waitcnt lgkmcnt(11)
	v_mfma_f32_32x32x16_bf16 v[154:169], v[110:113], v[6:9], v[154:169]
	ds_read_b128 v[110:113], v85 offset:16384
	v_exp_f32_e32 v148, v148
	v_exp_f32_e32 v149, v149
	s_waitcnt lgkmcnt(11)
	v_mfma_f32_32x32x16_bf16 v[18:33], v[128:131], v[114:117], v[18:33]
	v_exp_f32_e32 v150, v150
	v_exp_f32_e32 v151, v151
	s_waitcnt lgkmcnt(10)
	v_mfma_f32_32x32x16_bf16 v[34:49], v[184:187], v[114:117], v[34:49]
	v_exp_f32_e32 v152, v152
	v_exp_f32_e32 v153, v153
	s_waitcnt lgkmcnt(9)
	v_mfma_f32_32x32x16_bf16 v[50:65], v[188:191], v[114:117], v[50:65]
	v_add_f32_e32 v122, v146, v122
	v_add_f32_e32 v122, v147, v122
	v_add_f32_e32 v122, v148, v122
	v_add_f32_e32 v122, v149, v122
	s_waitcnt lgkmcnt(8)
	v_mfma_f32_32x32x16_bf16 v[66:81], v[192:195], v[114:117], v[66:81]
	v_add_f32_e32 v122, v150, v122
	v_add_f32_e32 v122, v151, v122
	v_add_f32_e32 v122, v152, v122
	v_add_f32_e32 v122, v153, v122
	v_cvt_pk_bf16_f32 v118, v146, v147
	v_cvt_pk_bf16_f32 v119, v148, v149
	v_cvt_pk_bf16_f32 v120, v150, v151
	v_cvt_pk_bf16_f32 v121, v152, v153
	ds_read_b128 v[128:131], v88 offset:0
	ds_read_b128 v[184:187], v88 offset:8192
	ds_read_b128 v[188:191], v88 offset:16384
	ds_read_b128 v[192:195], v88 offset:24576
	s_waitcnt lgkmcnt(11)
	v_mfma_f32_32x32x16_bf16 v[138:153], v[98:101], v[10:13], 0
	ds_read_b128 v[98:101], v82 offset:24576
	v_exp_f32_e32 v154, v154
	v_exp_f32_e32 v155, v155
	s_waitcnt lgkmcnt(11)
	v_mfma_f32_32x32x16_bf16 v[138:153], v[102:105], v[14:17], v[138:153]
	ds_read_b128 v[102:105], v83 offset:24576
	v_exp_f32_e32 v156, v156
	v_exp_f32_e32 v157, v157
	s_waitcnt lgkmcnt(11)
	v_mfma_f32_32x32x16_bf16 v[18:33], v[196:199], v[118:121], v[18:33]
	v_exp_f32_e32 v158, v158
	v_exp_f32_e32 v159, v159
	s_waitcnt lgkmcnt(10)
	v_mfma_f32_32x32x16_bf16 v[34:49], v[216:219], v[118:121], v[34:49]
	v_exp_f32_e32 v160, v160
	v_exp_f32_e32 v161, v161
	s_waitcnt lgkmcnt(9)
	v_mfma_f32_32x32x16_bf16 v[50:65], v[200:203], v[118:121], v[50:65]
	v_add_f32_e32 v122, v154, v122
	v_add_f32_e32 v122, v155, v122
	v_add_f32_e32 v122, v156, v122
	v_add_f32_e32 v122, v157, v122
	s_waitcnt lgkmcnt(8)
	v_mfma_f32_32x32x16_bf16 v[66:81], v[204:207], v[118:121], v[66:81]
	v_add_f32_e32 v122, v158, v122
	v_add_f32_e32 v122, v159, v122
	v_add_f32_e32 v122, v160, v122
	v_add_f32_e32 v122, v161, v122
	v_cvt_pk_bf16_f32 v114, v154, v155
	v_cvt_pk_bf16_f32 v115, v156, v157
	v_cvt_pk_bf16_f32 v116, v158, v159
	v_cvt_pk_bf16_f32 v117, v160, v161
	ds_read_b128 v[196:199], v89 offset:0
	ds_read_b128 v[216:219], v89 offset:8192
	ds_read_b128 v[200:203], v89 offset:16384
	ds_read_b128 v[204:207], v89 offset:24576
	s_waitcnt lgkmcnt(11)
	v_mfma_f32_32x32x16_bf16 v[138:153], v[106:109], v[2:5], v[138:153]
	ds_read_b128 v[106:109], v84 offset:24576
	v_exp_f32_e32 v162, v162
	v_exp_f32_e32 v163, v163
	s_waitcnt lgkmcnt(11)
	v_mfma_f32_32x32x16_bf16 v[138:153], v[110:113], v[6:9], v[138:153]
	ds_read_b128 v[110:113], v85 offset:24576
	v_exp_f32_e32 v164, v164
	v_exp_f32_e32 v165, v165
	s_waitcnt lgkmcnt(11)
	v_mfma_f32_32x32x16_bf16 v[18:33], v[128:131], v[114:117], v[18:33]
	v_exp_f32_e32 v166, v166
	v_exp_f32_e32 v167, v167
	s_waitcnt lgkmcnt(10)
	v_mfma_f32_32x32x16_bf16 v[34:49], v[184:187], v[114:117], v[34:49]
	v_exp_f32_e32 v168, v168
	v_exp_f32_e32 v169, v169
	s_waitcnt lgkmcnt(9)
	v_mfma_f32_32x32x16_bf16 v[50:65], v[188:191], v[114:117], v[50:65]
	v_add_f32_e32 v122, v162, v122
	v_add_f32_e32 v122, v163, v122
	v_add_f32_e32 v122, v164, v122
	v_add_f32_e32 v122, v165, v122
	s_waitcnt lgkmcnt(8)
	v_mfma_f32_32x32x16_bf16 v[66:81], v[192:195], v[114:117], v[66:81]
	v_add_f32_e32 v122, v166, v122
	v_add_f32_e32 v122, v167, v122
	v_add_f32_e32 v122, v168, v122
	v_add_f32_e32 v122, v169, v122
	v_cvt_pk_bf16_f32 v118, v162, v163
	v_cvt_pk_bf16_f32 v119, v164, v165
	v_cvt_pk_bf16_f32 v120, v166, v167
	v_cvt_pk_bf16_f32 v121, v168, v169
	ds_read_b128 v[128:131], v90 offset:0
	ds_read_b128 v[184:187], v90 offset:8192
	ds_read_b128 v[188:191], v90 offset:16384
	ds_read_b128 v[192:195], v90 offset:24576
	s_waitcnt lgkmcnt(11)
	v_mfma_f32_32x32x16_bf16 v[154:169], v[98:101], v[10:13], 0
	v_exp_f32_e32 v138, v138
	v_exp_f32_e32 v139, v139
	s_waitcnt lgkmcnt(10)
	v_mfma_f32_32x32x16_bf16 v[154:169], v[102:105], v[14:17], v[154:169]
	v_exp_f32_e32 v140, v140
	v_exp_f32_e32 v141, v141
	s_waitcnt lgkmcnt(9)
	v_mfma_f32_32x32x16_bf16 v[18:33], v[196:199], v[118:121], v[18:33]
	v_exp_f32_e32 v142, v142
	v_exp_f32_e32 v143, v143
	s_waitcnt lgkmcnt(8)
	v_mfma_f32_32x32x16_bf16 v[34:49], v[216:219], v[118:121], v[34:49]
	v_exp_f32_e32 v144, v144
	v_exp_f32_e32 v145, v145
	s_waitcnt lgkmcnt(7)
	v_mfma_f32_32x32x16_bf16 v[50:65], v[200:203], v[118:121], v[50:65]
	v_add_f32_e32 v122, v138, v122
	v_add_f32_e32 v122, v139, v122
	v_add_f32_e32 v122, v140, v122
	v_add_f32_e32 v122, v141, v122
	s_waitcnt lgkmcnt(6)
	v_mfma_f32_32x32x16_bf16 v[66:81], v[204:207], v[118:121], v[66:81]
	v_add_f32_e32 v122, v142, v122
	v_add_f32_e32 v122, v143, v122
	v_add_f32_e32 v122, v144, v122
	v_add_f32_e32 v122, v145, v122
	v_cvt_pk_bf16_f32 v114, v138, v139
	v_cvt_pk_bf16_f32 v115, v140, v141
	v_cvt_pk_bf16_f32 v116, v142, v143
	v_cvt_pk_bf16_f32 v117, v144, v145
	ds_read_b128 v[196:199], v91 offset:0
	ds_read_b128 v[216:219], v91 offset:8192
	ds_read_b128 v[200:203], v91 offset:16384
	ds_read_b128 v[204:207], v91 offset:24576
	s_waitcnt lgkmcnt(9)
	v_mfma_f32_32x32x16_bf16 v[154:169], v[106:109], v[2:5], v[154:169]
	v_exp_f32_e32 v146, v146
	v_exp_f32_e32 v147, v147
	s_waitcnt lgkmcnt(8)
	v_mfma_f32_32x32x16_bf16 v[154:169], v[110:113], v[6:9], v[154:169]
	v_exp_f32_e32 v148, v148
	v_exp_f32_e32 v149, v149
	s_waitcnt lgkmcnt(7)
	v_mfma_f32_32x32x16_bf16 v[18:33], v[128:131], v[114:117], v[18:33]
	v_exp_f32_e32 v150, v150
	v_exp_f32_e32 v151, v151
	s_waitcnt lgkmcnt(6)
	v_mfma_f32_32x32x16_bf16 v[34:49], v[184:187], v[114:117], v[34:49]
	v_exp_f32_e32 v152, v152
	v_exp_f32_e32 v153, v153
	s_waitcnt lgkmcnt(5)
	v_mfma_f32_32x32x16_bf16 v[50:65], v[188:191], v[114:117], v[50:65]
	v_add_f32_e32 v122, v146, v122
	v_add_f32_e32 v122, v147, v122
	v_add_f32_e32 v122, v148, v122
	v_add_f32_e32 v122, v149, v122
	s_waitcnt lgkmcnt(4)
	v_mfma_f32_32x32x16_bf16 v[66:81], v[192:195], v[114:117], v[66:81]
	v_add_f32_e32 v122, v150, v122
	v_add_f32_e32 v122, v151, v122
	v_add_f32_e32 v122, v152, v122
	v_add_f32_e32 v122, v153, v122
	v_cvt_pk_bf16_f32 v118, v146, v147
	v_cvt_pk_bf16_f32 v119, v148, v149
	v_cvt_pk_bf16_f32 v120, v150, v151
	v_cvt_pk_bf16_f32 v121, v152, v153
	ds_read_b128 v[128:131], v92 offset:0
	ds_read_b128 v[184:187], v92 offset:8192
	ds_read_b128 v[188:191], v92 offset:16384
	ds_read_b128 v[192:195], v92 offset:24576
	s_waitcnt lgkmcnt(7)
	v_mfma_f32_32x32x16_bf16 v[18:33], v[196:199], v[118:121], v[18:33]
	v_exp_f32_e32 v154, v154
	v_exp_f32_e32 v155, v155
	v_exp_f32_e32 v156, v156
	s_waitcnt lgkmcnt(6)
	v_mfma_f32_32x32x16_bf16 v[34:49], v[216:219], v[118:121], v[34:49]
	v_exp_f32_e32 v157, v157
	v_exp_f32_e32 v158, v158
	v_exp_f32_e32 v159, v159
	v_exp_f32_e32 v160, v160
	s_waitcnt lgkmcnt(5)
	v_mfma_f32_32x32x16_bf16 v[50:65], v[200:203], v[118:121], v[50:65]
	v_exp_f32_e32 v161, v161
	v_add_f32_e32 v122, v154, v122
	v_add_f32_e32 v122, v155, v122
	v_add_f32_e32 v122, v156, v122
	v_add_f32_e32 v122, v157, v122
	v_add_f32_e32 v122, v158, v122
	s_waitcnt lgkmcnt(4)
	v_mfma_f32_32x32x16_bf16 v[66:81], v[204:207], v[118:121], v[66:81]
	v_add_f32_e32 v122, v159, v122
	v_add_f32_e32 v122, v160, v122
	v_add_f32_e32 v122, v161, v122
	v_xor_b32_e32 v82, 0x8000, v82
	v_xor_b32_e32 v83, 0x8000, v83
	v_xor_b32_e32 v84, 0x8000, v84
	v_xor_b32_e32 v85, 0x8000, v85
	v_cvt_pk_bf16_f32 v114, v154, v155
	v_cvt_pk_bf16_f32 v115, v156, v157
	v_cvt_pk_bf16_f32 v116, v158, v159
	v_cvt_pk_bf16_f32 v117, v160, v161
	ds_read_b128 v[196:199], v93 offset:0
	ds_read_b128 v[216:219], v93 offset:8192
	ds_read_b128 v[200:203], v93 offset:16384
	ds_read_b128 v[204:207], v93 offset:24576
	s_waitcnt lgkmcnt(7)
	v_mfma_f32_32x32x16_bf16 v[18:33], v[128:131], v[114:117], v[18:33]
	v_exp_f32_e32 v162, v162
	v_exp_f32_e32 v163, v163
	v_exp_f32_e32 v164, v164
	s_waitcnt lgkmcnt(6)
	v_mfma_f32_32x32x16_bf16 v[34:49], v[184:187], v[114:117], v[34:49]
	v_exp_f32_e32 v165, v165
	v_exp_f32_e32 v166, v166
	v_exp_f32_e32 v167, v167
	s_waitcnt lgkmcnt(5)
	v_mfma_f32_32x32x16_bf16 v[50:65], v[188:191], v[114:117], v[50:65]
	v_exp_f32_e32 v168, v168
	v_exp_f32_e32 v169, v169
	v_add_f32_e32 v122, v162, v122
	v_add_f32_e32 v122, v163, v122
	s_waitcnt lgkmcnt(4)
	v_mfma_f32_32x32x16_bf16 v[66:81], v[192:195], v[114:117], v[66:81]
	v_add_f32_e32 v122, v164, v122
	v_add_f32_e32 v122, v165, v122
	v_add_f32_e32 v122, v166, v122
	v_add_f32_e32 v122, v167, v122
	v_add_f32_e32 v122, v168, v122
	v_add_f32_e32 v122, v169, v122
	v_cvt_pk_bf16_f32 v118, v162, v163
	v_cvt_pk_bf16_f32 v119, v164, v165
	v_cvt_pk_bf16_f32 v120, v166, v167
	v_cvt_pk_bf16_f32 v121, v168, v169
	v_xor_b32_e32 v86, 0x8000, v86
	v_xor_b32_e32 v87, 0x8000, v87
	v_xor_b32_e32 v88, 0x8000, v88
	v_xor_b32_e32 v89, 0x8000, v89
	v_xor_b32_e32 v90, 0x8000, v90
	v_xor_b32_e32 v91, 0x8000, v91
	v_xor_b32_e32 v92, 0x8000, v92
	v_xor_b32_e32 v93, 0x8000, v93
	s_waitcnt vmcnt(0)
	s_waitcnt lgkmcnt(0)
	s_barrier
	s_add_i32 s15, s15, 1
	s_cmp_eq_u32 s15, 34
	s_cbranch_scc0 .Lattn_nf_loop
	v_mfma_f32_32x32x16_bf16 v[18:33], v[196:199], v[118:121], v[18:33]
	v_mfma_f32_32x32x16_bf16 v[34:49], v[216:219], v[118:121], v[34:49]
	v_mfma_f32_32x32x16_bf16 v[50:65], v[200:203], v[118:121], v[50:65]
	v_mfma_f32_32x32x16_bf16 v[66:81], v[204:207], v[118:121], v[66:81]
	v_readlane_b32 s64, v175, 0
	v_readlane_b32 s65, v175, 1
	v_readlane_b32 s66, v175, 2
	v_readlane_b32 s67, v175, 3
	v_readlane_b32 s68, v175, 4
	v_readlane_b32 s69, v175, 5
	v_readlane_b32 s70, v175, 6
	v_readlane_b32 s71, v175, 7
	v_readlane_b32 s72, v175, 8
	v_readlane_b32 s73, v175, 9
	v_readlane_b32 s74, v175, 10
	v_readlane_b32 s75, v175, 11
	v_readlane_b32 s76, v175, 12
	v_readlane_b32 s77, v175, 13
	v_readlane_b32 s78, v175, 14
	v_readlane_b32 s79, v175, 15
	s_nop 4
	s_mov_b32 s10, 0x3fb8aa3b
	s_mov_b32 s11, 0xc2ce8ed0
	s_mov_b32 s6, 0x42b17218
	v_cmp_eq_u32_e64 s[40:41], 0, v179
	s_lshl_b32 s30, s14, 1
	v_lshlrev_b32_e32 v196, 3, v178
	v_mov_b32_e32 v197, 0
	v_lshlrev_b32_e32 v198, 4, v179
	v_or3_b32 v198, v198, v177, v180
	v_ashrrev_i32_e32 v199, 31, v198
	v_lshlrev_b64 v[198:199], 11, v[198:199]
	s_mov_b64 s[100:101], 0x18a10000
	v_lshl_add_u64 v[198:199], s[42:43], 0, v[198:199]
	v_lshl_add_u64 v[198:199], v[198:199], 0, s[30:31]
	v_lshl_add_u64 v[198:199], v[198:199], 0, v[196:197]
	v_lshl_add_u64 v[198:199], v[198:199], 0, s[100:101]
	global_load_dwordx2 v[146:147], v[198:199], off
	global_load_dwordx2 v[148:149], v[198:199], off offset:32
	global_load_dwordx2 v[150:151], v[198:199], off offset:64
	global_load_dwordx2 v[152:153], v[198:199], off offset:96
	global_load_dwordx2 v[188:189], v[198:199], off offset:128
	global_load_dwordx2 v[190:191], v[198:199], off offset:160
	global_load_dwordx2 v[192:193], v[198:199], off offset:192
	global_load_dwordx2 v[194:195], v[198:199], off offset:224
	s_mov_b64 s[100:101], exec
	s_and_b64 exec, exec, s[4:5]
	s_cbranch_execz .Lpop_skip
	v_readlane_b32 s14, v255, 22
	v_readlane_b32 s15, v255, 23
	v_mov_b32_e32 v224, 1
	s_nop 4
	global_atomic_add v224, v0, v224, s[14:15] sc0
